# v25 + attention loop exact vmcnt (no wait for previous item's O/LSE store acks), retest on contiguous item blocks
# speedup vs baseline: 1.0033x; 1.0005x over previous
; __device__ __forceinline__ int ltid(int wave) { int t = (wave << 6) | (int)__builtin_amdgcn_mbcnt_hi(~0u, __builtin_amdgcn_mbcnt_lo(~0u, 0u)); asm volatile("" : "+v"(t)); return t; }
; __device__ __forceinline__ int lbid() { int b = blockIdx.x; asm volatile("" : "+s"(b)); return b; }
; __device__ void attn_items(const Params& p, unsigned char* shm) {
;     ...
;     const int tid = ltid(p.wave), lane = tid & 63, w = tid >> 6, fr = lane & 15, fq = lane >> 4, G_ = gridDim.x;
;     for (int i = tid; i < 24 * 129; i += 512) { const int hd = i / 129, j = i % 129; BT[hd * 132 + j] = p.in[21][(int)BUCKET[hd >> 3][j] * 24 + hd]; }
;     u32x4 kreg[5], vreg[5]; bf16x8 q0r, q1r;
;     const int total = 24 * 192;
;     int it = lbid();
;     ...
;         for (int i = 0; i < 4; ++i) { const int qi = fq * 4 + i; float m = -3.0e38f;
; #pragma unroll
;             for (int kt = 0; kt < 9; ++kt) { const int rel = 16 * kt + fr - 64 - qi, klat = G.q0 - 64 + 16 * w + 16 * kt + fr;
;                 const bool ok = rel >= -64 && rel <= 64 && klat >= 0 && klat < G.n_lat; const int bi = min(max(rel + 64, 0), 128);
;                 const float v = ok ? s[kt][i] + bs[bi] : -1.0e30f; s[kt][i] = v; m = fmaxf(m, v); }
;             m = fmaxf(m, __shfl_xor(m, 1)); m = fmaxf(m, __shfl_xor(m, 2)); m = fmaxf(m, __shfl_xor(m, 4)); m = fmaxf(m, __shfl_xor(m, 8));
;             float sum = 0.f;
; #pragma unroll
;             for (int kt = 0; kt < 9; ++kt) { const float pv = __expf(s[kt][i] - m); s[kt][i] = pv; sum += pv; }
;             sum += __shfl_xor(sum, 1); sum += __shfl_xor(sum, 2); sum += __shfl_xor(sum, 4); sum += __shfl_xor(sum, 8);
;             mx[i] = m; ls[i] = sum; }
.LBB0_338:
	v_and_b32_e32 v2, 63, v130
	s_movk_i32 s22, 0xc00
	s_andn2_b64 vcc, exec, s[40:41]
	s_cbranch_vccnz .LBB0_453
	v_and_b32_e32 v0, 48, v130
	v_and_b32_e32 v50, 64, v140
	v_add_u32_e32 v101, 0, v0
	v_xor_b32_e32 v0, 1, v140
	v_add_u32_e32 v50, 64, v50
	v_cmp_lt_i32_e32 vcc, v0, v50
	s_movk_i32 s0, 0x1500
	v_lshlrev_b32_e32 v99, 4, v47
	v_cndmask_b32_e32 v0, v140, v0, vcc
	v_lshlrev_b32_e32 v103, 2, v0
	v_xor_b32_e32 v0, 2, v140
	v_cmp_lt_i32_e32 vcc, v0, v50
	v_and_b32_e32 v92, 56, v48
	v_lshlrev_b32_e32 v51, 4, v46
	v_cndmask_b32_e32 v0, v140, v0, vcc
	v_lshlrev_b32_e32 v104, 2, v0
	v_xor_b32_e32 v0, 4, v140
	v_cmp_lt_i32_e32 vcc, v0, v50
	s_mov_b64 s[86:87], s[90:91]
	v_add_u32_e32 v61, 0x200, v130
	v_cndmask_b32_e32 v0, v140, v0, vcc
	v_lshlrev_b32_e32 v105, 2, v0
	v_xor_b32_e32 v0, 8, v140
	v_cmp_lt_i32_e32 vcc, v0, v50
	v_ashrrev_i32_e32 v110, 3, v61
	s_movk_i32 s1, 0x680
	v_cndmask_b32_e32 v0, v140, v0, vcc
	v_lshlrev_b32_e32 v106, 2, v0
	v_mul_lo_u32 v0, v47, s0
	v_readlane_b32 s0, v254, 9
	v_cmp_gt_i32_e64 s[42:43], s1, v130
	v_add_u32_e32 v63, 0x400, v130
	v_add_u32_e32 v47, s0, v0
	s_movk_i32 s0, 0x880
	v_cmp_gt_i32_e64 s[6:7], s0, v130
	s_movk_i32 s0, 0x100
	v_mul_u32_u24_e32 v0, 0x150, v93
	v_cmp_gt_i32_e64 s[8:9], s0, v98
	v_add3_u32 v107, v47, v0, v51
	v_lshlrev_b32_e32 v0, 1, v92
	v_writelane_b32 v255, s8, 10
	v_lshl_add_u64 v[94:95], s[90:91], 0, v[0:1]
	s_mov_b64 s[90:91], s[6:7]
	v_writelane_b32 v255, s9, 11
	s_and_b64 s[6:7], s[6:7], s[8:9]
	v_writelane_b32 v255, s6, 14
	v_cmp_gt_i32_e64 s[18:19], s0, v110
	v_ashrrev_i32_e32 v111, 3, v63
	v_writelane_b32 v255, s7, 15
	v_writelane_b32 v255, s18, 16
	s_and_b64 s[6:7], s[42:43], s[18:19]
	s_movk_i32 s1, 0x480
	v_writelane_b32 v255, s19, 17
	v_writelane_b32 v255, s6, 18
	v_cmp_gt_i32_e64 s[38:39], s0, v111
	v_cmp_gt_i32_e64 s[46:47], s1, v130
	v_writelane_b32 v255, s7, 19
	v_writelane_b32 v255, s38, 20
	v_add_u32_e32 v65, 0x600, v130
	s_and_b64 s[6:7], s[46:47], s[38:39]
	v_writelane_b32 v255, s39, 21
	v_ashrrev_i32_e32 v112, 3, v65
	v_writelane_b32 v255, s6, 22
	s_movk_i32 s3, 0x280
	v_cmp_gt_i32_e64 s[40:41], s0, v112
	v_writelane_b32 v255, s7, 23
	v_cmp_gt_i32_e64 s[50:51], s3, v130
	v_writelane_b32 v255, s40, 24
	v_add_u32_e32 v67, 0x800, v130
	s_and_b64 s[6:7], s[50:51], s[40:41]
	v_writelane_b32 v255, s41, 25
	v_ashrrev_i32_e32 v113, 3, v67
	s_movk_i32 s1, 0x80
	v_writelane_b32 v255, s6, 26
	v_cmp_gt_i32_e64 s[54:55], s1, v130
	v_cmp_gt_i32_e64 s[0:1], s0, v113
	v_writelane_b32 v255, s7, 27
	v_lshlrev_b32_e32 v48, 2, v46
	v_writelane_b32 v255, s0, 28
	v_sub_u32_e32 v115, v93, v48
	v_add_u32_e32 v76, 0x80, v115
	v_writelane_b32 v255, s1, 29
	s_and_b64 s[0:1], s[54:55], s[0:1]
	v_writelane_b32 v255, s0, 30
	v_or_b32_e32 v77, 2, v48
	v_sub_u32_e32 v118, v93, v77
	v_writelane_b32 v255, s1, 31
	s_movk_i32 s0, 0x81
	v_cmp_gt_u32_e64 s[6:7], s0, v115
	v_add_u32_e32 v119, 0x80, v118
	v_or_b32_e32 v108, v48, v99
	v_writelane_b32 v254, s6, 49
	v_lshl_add_u32 v50, v93, 1, v47
	v_lshlrev_b32_e32 v44, 3, v46
	v_writelane_b32 v254, s7, 50
	v_cmp_gt_u32_e64 s[6:7], s0, v76
	v_or_b32_e32 v76, 1, v48
	v_sub_u32_e32 v116, v93, v76
	v_writelane_b32 v254, s6, 37
	v_add_u32_e32 v117, 0x80, v116
	v_or_b32_e32 v48, 3, v48
	v_writelane_b32 v254, s7, 38
	v_cmp_gt_u32_e64 s[6:7], s0, v116
	v_sub_u32_e32 v120, v93, v48
	v_add_u32_e32 v121, 0x80, v120
	v_writelane_b32 v255, s6, 0
	v_add_u32_e32 v51, v44, v99
	v_mul_u32_u24_e32 v48, 0x540, v46
	v_writelane_b32 v255, s7, 1
	v_cmp_gt_u32_e64 s[6:7], s0, v117
	v_or_b32_e32 v127, 16, v93
	v_bitop3_b32 v78, v51, v127, 24 bitop3:0x78
	v_writelane_b32 v255, s6, 2
	v_or_b32_e32 v129, 32, v93
	v_bitop3_b32 v79, v51, v129, 40 bitop3:0x78
	v_writelane_b32 v255, s7, 3
	v_cmp_gt_u32_e64 s[6:7], s0, v118
	v_or_b32_e32 v132, 48, v93
	v_bitop3_b32 v80, v51, v132, 56 bitop3:0x78
	v_writelane_b32 v255, s6, 4
	v_and_b32_e32 v3, 7, v130
	v_lshlrev_b32_e32 v49, 3, v3
	v_writelane_b32 v255, s7, 5
	v_cmp_gt_u32_e64 s[6:7], s0, v119
	v_or_b32_e32 v100, v99, v93
	v_lshrrev_b32_e32 v109, 3, v2
	v_writelane_b32 v255, s6, 6
	s_movk_i32 s2, 0x90
	v_xor_b32_e32 v60, v49, v98
; __device__ void attn_items(const Params& p, unsigned char* shm) {
;     ...
; #pragma unroll
;         for (int i = 0; i < 5; ++i) { const int e = tid + 512 * i, kk = e >> 3, c8 = e & 7;
;             if (e < 2176) {
;                 if (kk < 256) *(u32x4*)(Ks + kk * 72 + c8 * 8) = kreg[i];
; #pragma unroll
;                 for (int j = 0; j < 8; ++j) Vt[(c8 * 8 + j) * 320 + (kk ^ (c8 << 3))] = (bf16_t)((vreg[i][j >> 1] >> ((j & 1) * 16)) & 0xffffu); } }
;         const bf16x8 aq0 = q0r, aq1 = q1r;
;         __syncthreads();
;         if (it + G_ < total) ATT_LOAD(it + G_);
;         asm volatile("" ::: "memory");
;         const float* bs = BT + G.hd * 132;
;         f32x4 s[9];
; #pragma unroll
;         for (int kt = 0; kt < 9; ++kt) { const bf16_t* kr = Ks + (16 * w + 16 * kt + fr) * 72 + fq * 8;
;             f32x4 a = (f32x4){0.f, 0.f, 0.f, 0.f};
;             a = __builtin_amdgcn_mfma_f32_16x16x32_bf16(aq0, *(const bf16x8*)kr, a, 0, 0, 0);
;             a = __builtin_amdgcn_mfma_f32_16x16x32_bf16(aq1, *(const bf16x8*)(kr + 32), a, 0, 0, 0); s[kt] = a; }
;         float mx[4], ls[4];
; #pragma unroll
;         for (int i = 0; i < 4; ++i) { const int qi = fq * 4 + i; float m = -3.0e38f;
; #pragma unroll
;             for (int kt = 0; kt < 9; ++kt) { const int rel = 16 * kt + fr - 64 - qi, klat = G.q0 - 64 + 16 * w + 16 * kt + fr;
;                 const bool ok = rel >= -64 && rel <= 64 && klat >= 0 && klat < G.n_lat; const int bi = min(max(rel + 64, 0), 128);
;                 const float v = ok ? s[kt][i] + bs[bi] : -1.0e30f; s[kt][i] = v; m = fmaxf(m, v); }
;             m = fmaxf(m, __shfl_xor(m, 1)); m = fmaxf(m, __shfl_xor(m, 2)); m = fmaxf(m, __shfl_xor(m, 4)); m = fmaxf(m, __shfl_xor(m, 8));
;             float sum = 0.f;
; #pragma unroll
;             for (int kt = 0; kt < 9; ++kt) { const float pv = __expf(s[kt][i] - m); s[kt][i] = pv; sum += pv; }
;             sum += __shfl_xor(sum, 1); sum += __shfl_xor(sum, 2); sum += __shfl_xor(sum, 4); sum += __shfl_xor(sum, 8);
;             mx[i] = m; ls[i] = sum; }
;         bf16_t* Pw = Ps + w * 16 * 168;
; #pragma unroll
;         for (int i = 0; i < 4; ++i) {
; #pragma unroll
;             for (int kt = 0; kt < 9; ++kt) Pw[(fq * 4 + i) * 168 + 16 * kt + fr] = f2bf(s[kt][i]);
;             Pw[(fq * 4 + i) * 168 + 144 + fr] = 0; }
;         __syncthreads();
;         f32x4 o[4];
; #pragma unroll
	v_writelane_b32 v255, s7, 7
	v_cmp_gt_u32_e64 s[6:7], s0, v120
	v_cmp_gt_u32_e64 s[0:1], s0, v121
	v_xor_b32_e32 v62, v110, v49
	v_writelane_b32 v255, s6, 12
	v_xor_b32_e32 v64, v111, v49
	v_xor_b32_e32 v66, v112, v49
	v_writelane_b32 v255, s7, 13
	v_writelane_b32 v255, s0, 8
	v_xor_b32_e32 v49, v113, v49
	v_mul_lo_u32 v114, v100, s2
	v_writelane_b32 v255, s1, 9
	s_movk_i32 s0, 0x540
	v_mad_u32_u24 v122, v46, s0, v50
	s_movk_i32 s0, 0x150
	v_mad_u32_u24 v77, v76, s0, s0
	v_add_u32_e32 v124, v50, v77
	v_mov_b32_e32 v77, 0x2a0
	v_mul_u32_u24_e32 v46, 0x150, v76
	v_mad_u32_u24 v123, v76, s0, v50
	v_mad_u32_u24 v76, v76, s0, v77
	v_add_u32_e32 v125, v50, v76
	v_mad_u32_u24 v76, v93, s3, 0
	v_bitop3_b32 v77, v51, v130, 8 bitop3:0x78
	v_lshl_add_u32 v126, v77, 1, v76
	v_add_u32_e32 v77, 0x2800, v76
	v_lshl_add_u32 v128, v78, 1, v77
	v_add_u32_e32 v78, 0x5000, v76
	v_lshl_add_u32 v131, v79, 1, v78
	v_add_u32_e32 v79, 0x7800, v76
	v_lshl_add_u32 v133, v80, 1, v79
	v_add_u32_e32 v80, 32, v51
	v_bitop3_b32 v81, v80, v130, 8 bitop3:0x78
	v_lshl_add_u32 v134, v81, 1, v76
	v_bitop3_b32 v81, v80, v127, 24 bitop3:0x78
	v_lshl_add_u32 v135, v81, 1, v77
	v_bitop3_b32 v81, v80, v129, 40 bitop3:0x78
	v_bitop3_b32 v80, v80, v132, 56 bitop3:0x78
	v_lshl_add_u32 v137, v80, 1, v79
	v_add_u32_e32 v80, 64, v51
	v_lshl_add_u32 v136, v81, 1, v78
	v_bitop3_b32 v81, v80, v130, 8 bitop3:0x78
	v_lshl_add_u32 v138, v81, 1, v76
	v_bitop3_b32 v81, v80, v127, 24 bitop3:0x78
	v_lshl_add_u32 v139, v81, 1, v77
	v_bitop3_b32 v81, v80, v129, 40 bitop3:0x78
	v_bitop3_b32 v80, v80, v132, 56 bitop3:0x78
	v_lshl_add_u32 v141, v80, 1, v79
	v_add_u32_e32 v80, 0x60, v51
	v_lshl_add_u32 v140, v81, 1, v78
	v_bitop3_b32 v81, v80, v130, 8 bitop3:0x78
	v_lshl_add_u32 v142, v81, 1, v76
	v_bitop3_b32 v81, v80, v127, 24 bitop3:0x78
	v_lshl_add_u32 v143, v81, 1, v77
	v_bitop3_b32 v81, v80, v129, 40 bitop3:0x78
	v_bitop3_b32 v80, v80, v132, 56 bitop3:0x78
	v_add_u32_e32 v51, 0x80, v51
	v_lshl_add_u32 v145, v80, 1, v79
	v_bitop3_b32 v80, v51, v130, 8 bitop3:0x78
	v_lshl_add_u32 v130, v80, 1, v76
	v_bitop3_b32 v76, v51, v127, 24 bitop3:0x78
	v_lshl_add_u32 v146, v76, 1, v77
	v_bitop3_b32 v76, v51, v129, 40 bitop3:0x78
	v_bitop3_b32 v51, v51, v132, 56 bitop3:0x78
	v_or_b32_e32 v149, 8, v109
	v_lshl_add_u32 v45, v3, 4, 0
	v_add_u32_e32 v47, v47, v0
	v_mul_u32_u24_e32 v0, 0x150, v109
	v_mul_lo_u32 v2, v98, s2
	v_lshl_add_u32 v60, v60, 1, 0
	v_mul_u32_u24_e32 v3, 0x1400, v3
	v_mul_lo_u32 v61, v110, s2
	v_lshl_add_u32 v62, v62, 1, 0
	v_mul_lo_u32 v63, v111, s2
	v_lshl_add_u32 v64, v64, 1, 0
	v_mul_lo_u32 v65, v112, s2
	v_lshl_add_u32 v66, v66, 1, 0
	v_mul_lo_u32 v67, v113, s2
	v_lshl_add_u32 v49, v49, 1, 0
	v_add_u32_e32 v68, 0x900, v114
	v_add_u32_e32 v69, 0x1200, v114
	v_add_u32_e32 v70, 0x1b00, v114
	v_add_u32_e32 v71, 0x2400, v114
	v_add_u32_e32 v72, 0x2d00, v114
	v_add_u32_e32 v73, 0x3600, v114
	v_add_u32_e32 v74, 0x3f00, v114
	v_add_u32_e32 v75, 0x4800, v114
	v_lshl_add_u32 v148, v51, 1, v79
	v_mul_u32_u24_e32 v51, 0x150, v149
	v_readlane_b32 s0, v251, 10
	s_movk_i32 s23, 0xff7f
	v_subrev_u32_e32 v102, 64, v99
	v_cmp_eq_u32_e64 s[36:37], 0, v93
	v_lshl_add_u32 v144, v81, 1, v78
	v_lshl_add_u32 v147, v76, 1, v78
	v_or_b32_e32 v150, 0x50, v93
	v_or_b32_e32 v151, 0x60, v93
	v_or_b32_e32 v152, 0x70, v93
	v_or_b32_e32 v153, 0x80, v93
	s_lshl_b32 s2, s4, 7
	s_movk_i32 s3, 0x80
	v_add_u32_e32 v154, v45, v2
	v_add_u32_e32 v155, v60, v3
	v_add_u32_e32 v156, v45, v61
	v_add_u32_e32 v157, v62, v3
	v_add_u32_e32 v158, v45, v63
	v_add_u32_e32 v159, v64, v3
	v_add_u32_e32 v160, v45, v65
	v_add_u32_e32 v161, v66, v3
	v_add_u32_e32 v162, v45, v67
	v_add_u32_e32 v163, v49, v3
	v_lshlrev_b32_e32 v96, 1, v44
	v_add_u32_e32 v164, v101, v68
	v_add_u32_e32 v165, v101, v69
	v_add_u32_e32 v166, v101, v70
	v_add_u32_e32 v167, v101, v71
	v_add_u32_e32 v168, v101, v72
	v_add_u32_e32 v169, v101, v73
	v_add_u32_e32 v170, v101, v74
	v_add_u32_e32 v171, v101, v75
	v_add_u32_e32 v172, v50, v48
	v_add_u32_e32 v173, v47, v0
	v_add_u32_e32 v174, v47, v51
	v_add_u32_e32 v175, v50, v46
	v_readlane_b32 s1, v251, 11
	s_waitcnt vmcnt(0)
	s_branch .LBB0_341

; __device__ void attn_items(const Params& p, unsigned char* shm) {
;     ...
;     for (; it < total; it += G_) {
;         const AttnGeom G = attn_geom(it);
; #pragma unroll
;         for (int i = 0; i < 5; ++i) { const int e = tid + 512 * i, kk = e >> 3, c8 = e & 7;
;             if (e < 2176) {
;                 if (kk < 256) *(u32x4*)(Ks + kk * 72 + c8 * 8) = kreg[i];
; #pragma unroll
;                 for (int j = 0; j < 8; ++j) Vt[(c8 * 8 + j) * 320 + (kk ^ (c8 << 3))] = (bf16_t)((vreg[i][j >> 1] >> ((j & 1) * 16)) & 0xffffu); } }
;         const bf16x8 aq0 = q0r, aq1 = q1r;
;         __syncthreads();
;         if (it + G_ < total) ATT_LOAD(it + G_);
.LBB0_361:
	s_or_b64 exec, exec, s[0:1]
	s_add_i32 s15, s4, 1
	s_mul_i32 s0, s80, 18
	s_add_i32 s0, s0, 17
	s_cmp_gt_i32 s15, s0
	s_cselect_b64 s[40:41], -1, 0
	v_mov_b64_e32 v[44:45], v[56:57]
	v_mov_b64_e32 v[48:49], v[52:53]
	s_and_b64 vcc, exec, s[40:41]
	v_mov_b64_e32 v[46:47], v[58:59]
	v_mov_b64_e32 v[50:51], v[54:55]
	s_waitcnt lgkmcnt(0)
	s_barrier
	v_readlane_b32 s1, v251, 11
	s_cbranch_vccnz .LBB0_373
	s_mul_hi_i32 s0, s15, 0x2aaaaaab
	s_lshr_b32 s1, s0, 31
	s_ashr_i32 s0, s0, 5
	s_add_i32 s0, s0, s1
	s_mul_i32 s1, s0, 0xffffff40
	s_mul_i32 s5, s0, 0xffffa000
	s_add_i32 s6, s3, s2
	s_add_i32 s1, s15, s1
	s_add_i32 s6, s6, s5
	s_and_b32 s6, s6, 0xfffff800
	s_and_b32 s7, s1, 15
	s_sub_i32 s8, s1, 64
	s_and_b32 s5, s0, -8
	s_cmp_eq_u32 s5, 8
	s_cselect_b32 s5, 2, 4
	s_cmp_gt_u32 s0, 7
	s_cselect_b32 s5, s5, 0
	s_cmp_lt_i32 s1, 64
	s_cselect_b32 s1, s7, s8
	s_movk_i32 s7, 0x800
	s_cselect_b32 s7, s7, 0x4000
	s_cselect_b32 s10, s6, 0x2000
	s_cselect_b32 s6, 4, 7
	s_lshr_b32 s8, s7, s5
	s_lshr_b32 s7, s8, 7
	s_sub_i32 s6, s6, s5
	s_add_i32 s7, s7, -1
	s_lshr_b32 s17, s1, s6
	s_and_b32 s1, s7, s1
	s_lshl_b32 s6, s1, 7
	s_sub_i32 s9, s6, 64
	s_lshl_b32 s38, s0, 6
	v_add_u32_e32 v16, s9, v98
	v_readlane_b32 s0, v255, 14
	v_cmp_lt_i32_e32 vcc, -1, v16
	v_readlane_b32 s1, v255, 15
	v_mov_b32_e32 v2, v1
	v_mov_b32_e32 v3, v1
	v_mov_b32_e32 v6, v1
	v_mov_b32_e32 v7, v1
	s_ashr_i32 s39, s38, 31
	s_and_b64 s[0:1], s[0:1], vcc
	v_cmp_gt_i32_e32 vcc, s8, v16
	v_mov_b32_e32 v0, v1
	v_mov_b32_e32 v4, v1
	v_mov_b32_e32 v5, v1
	v_mov_b64_e32 v[14:15], v[6:7]
	v_mov_b64_e32 v[10:11], v[2:3]
	s_add_i32 s7, s17, s10
	v_mov_b32_e32 v45, s39
	v_or_b32_e32 v44, s38, v92
	s_and_b64 s[18:19], s[0:1], vcc
	v_mov_b64_e32 v[12:13], v[4:5]
	v_mov_b64_e32 v[8:9], v[0:1]
	s_and_saveexec_b64 s[0:1], s[18:19]
	s_cbranch_execz .LBB0_364
	v_lshlrev_b32_e32 v0, s5, v16
	v_add_u32_e32 v0, s7, v0
	v_mad_i64_i32 v[2:3], s[18:19], v0, s95, v[44:45]
	v_readlane_b32 s18, v252, 23
	v_lshlrev_b64 v[2:3], 1, v[2:3]
	v_readlane_b32 s19, v252, 24
	s_nop 1
	v_lshl_add_u64 v[8:9], s[18:19], 0, v[2:3]
	v_readlane_b32 s18, v252, 25
	v_readlane_b32 s19, v252, 26
	s_nop 1
	v_lshl_add_u64 v[2:3], s[18:19], 0, v[2:3]
	global_load_dwordx4 v[8:11], v[8:9], off
	s_nop 0
	global_load_dwordx4 v[12:15], v[2:3], off
